# v42 + EpiUp: 112 in-place i32->f32 conversions moved ahead of the first load wait (latency filler)
# speedup vs baseline: 1.0065x; 1.0004x over previous
;     __device__ __forceinline__ void operator()(Acc& acc, const Unit& u, int wr, int wc, int fr, int fq, LAS unsigned char* lds, int tid) const {
;     ...
;         if constexpr (I8) {
; #pragma unroll
;             for (int ai = 0; ai < 2; ++ai) { const f32x4 sa = ldf4(sx, tok0 + tl0 + 4u * ai);
; #pragma unroll
;                 for (int m = 0; m < 4; ++m)
; #pragma unroll
;                     for (int bj = 0; bj < 2; ++bj)
; #pragma unroll
;                         for (int n = 0; n < 2; ++n) { const pg8::i32x4 iv = __builtin_bit_cast(pg8::i32x4, acc[ai][bj][m][n]); acc[ai][bj][m][n] = __builtin_convertvector(iv, f32x4) * sa[m]; }
;                 asm volatile("" ::: "memory"); }
;         }
;         const unsigned bk = 2 * u.pm + wr;
;         const bool lvalid = (bk & 15) != 0, rvalid = (bk & 15) != 15;
; #pragma unroll
;         for (int bj = 0; bj < 2; ++bj) {
;             const unsigned colp = u.pn * 256 + bj * 128 + wc * 32 + 8 * fq;
;             const unsigned coll = bj * FF + u.pn * 128 + wc * 32 + 8 * fq;
; #pragma unroll
;             for (int n = 0; n < 2; ++n) {
;                 f32x4 c0 = ldf4(cw, coll + 4u * n), c1 = ldf4(cw, (unsigned)FF2 + coll + 4u * n), c2 = ldf4(cw, 2u * FF2 + coll + 4u * n);
;                 if constexpr (I8) { const f32x4 swv = ldf4(sw, colp + 4u * n); c0 = c0 * swv; c1 = c1 * swv; c2 = c2 * swv; }
;                 f32x4 hl = {0.f, 0.f, 0.f, 0.f}, hr = {0.f, 0.f, 0.f, 0.f};
;                 if (fr == 0 && lvalid) hl = ldf4(HALO, (2u * bk) * (unsigned)FF2 + colp + 4u * n);
;                 if (fr == 15 && rvalid) hr = ldf4(HALO, (2u * bk + 1u) * (unsigned)FF2 + colp + 4u * n);
.LBB0_1072:
	s_or_b64 exec, exec, s[60:61]
	v_mov_b32_e32 v147, v209
	v_lshl_add_u64 v[180:181], s[28:29], 0, v[146:147]
	v_cvt_f32_i32_e32 v147, v161
	v_cvt_f32_i32_e32 v146, v160
	v_cvt_f32_i32_e32 v161, v163
	v_cvt_f32_i32_e32 v160, v162
	v_lshl_add_u64 v[164:165], s[22:23], 0, v[208:209]
	v_cvt_f32_i32_e32 v149, v149
	v_cvt_f32_i32_e32 v148, v148
	v_cvt_f32_i32_e32 v153, v153
	v_cvt_f32_i32_e32 v152, v152
	v_cvt_f32_i32_e32 v155, v155
	v_cvt_f32_i32_e32 v154, v154
	v_cvt_f32_i32_e32 v151, v151
	v_cvt_f32_i32_e32 v150, v150
	v_cvt_f32_i32_e32 v117, v117
	v_cvt_f32_i32_e32 v116, v116
	v_cvt_f32_i32_e32 v109, v109
	v_cvt_f32_i32_e32 v108, v108
	v_cvt_f32_i32_e32 v119, v119
	v_cvt_f32_i32_e32 v118, v118
	v_cvt_f32_i32_e32 v111, v111
	v_cvt_f32_i32_e32 v110, v110
	v_cvt_f32_i32_e32 v53, v53
	v_cvt_f32_i32_e32 v52, v52
	v_cvt_f32_i32_e32 v49, v49
	v_cvt_f32_i32_e32 v48, v48
	v_cvt_f32_i32_e32 v45, v45
	v_cvt_f32_i32_e32 v44, v44
	v_cvt_f32_i32_e32 v41, v41
	v_cvt_f32_i32_e32 v40, v40
	v_cvt_f32_i32_e32 v37, v37
	v_cvt_f32_i32_e32 v36, v36
	v_cvt_f32_i32_e32 v33, v33
	v_cvt_f32_i32_e32 v32, v32
	v_cvt_f32_i32_e32 v55, v55
	v_cvt_f32_i32_e32 v54, v54
	v_cvt_f32_i32_e32 v51, v51
	v_cvt_f32_i32_e32 v50, v50
	v_cvt_f32_i32_e32 v47, v47
	v_cvt_f32_i32_e32 v46, v46
	v_cvt_f32_i32_e32 v43, v43
	v_cvt_f32_i32_e32 v42, v42
	v_cvt_f32_i32_e32 v39, v39
	v_cvt_f32_i32_e32 v38, v38
	v_cvt_f32_i32_e32 v27, v27
	v_cvt_f32_i32_e32 v26, v26
	v_cvt_f32_i32_e32 v13, v13
	v_cvt_f32_i32_e32 v12, v12
	v_cvt_f32_i32_e32 v35, v35
	v_cvt_f32_i32_e32 v34, v34
	v_cvt_f32_i32_e32 v101, v101
	v_cvt_f32_i32_e32 v100, v100
	v_cvt_f32_i32_e32 v97, v97
	v_cvt_f32_i32_e32 v96, v96
	v_cvt_f32_i32_e32 v93, v93
	v_cvt_f32_i32_e32 v92, v92
	v_cvt_f32_i32_e32 v11, v11
	v_cvt_f32_i32_e32 v10, v10
	v_cvt_f32_i32_e32 v89, v89
	v_cvt_f32_i32_e32 v88, v88
	v_cvt_f32_i32_e32 v31, v31
	v_cvt_f32_i32_e32 v30, v30
	v_cvt_f32_i32_e32 v17, v17
	v_cvt_f32_i32_e32 v16, v16
	v_cvt_f32_i32_e32 v85, v85
	v_cvt_f32_i32_e32 v84, v84
	v_cvt_f32_i32_e32 v77, v77
	v_cvt_f32_i32_e32 v79, v79
	v_cvt_f32_i32_e32 v78, v78
	v_cvt_f32_i32_e32 v76, v76
	v_cvt_f32_i32_e32 v57, v57
	v_cvt_f32_i32_e32 v59, v59
	v_cvt_f32_i32_e32 v58, v58
	v_cvt_f32_i32_e32 v56, v56
	v_cvt_f32_i32_e32 v7, v7
	v_cvt_f32_i32_e32 v6, v6
	v_cvt_f32_i32_e32 v103, v103
	v_cvt_f32_i32_e32 v102, v102
	v_cvt_f32_i32_e32 v99, v99
	v_cvt_f32_i32_e32 v98, v98
	v_cvt_f32_i32_e32 v95, v95
	v_cvt_f32_i32_e32 v94, v94
	v_cvt_f32_i32_e32 v91, v91
	v_cvt_f32_i32_e32 v90, v90
	v_cvt_f32_i32_e32 v87, v87
	v_cvt_f32_i32_e32 v86, v86
	v_cvt_f32_i32_e32 v81, v81
	v_cvt_f32_i32_e32 v80, v80
	v_cvt_f32_i32_e32 v73, v73
	v_cvt_f32_i32_e32 v72, v72
	v_cvt_f32_i32_e32 v69, v69
	v_cvt_f32_i32_e32 v68, v68
	v_cvt_f32_i32_e32 v65, v65
	v_cvt_f32_i32_e32 v64, v64
	v_cvt_f32_i32_e32 v61, v61
	v_cvt_f32_i32_e32 v60, v60
	v_cvt_f32_i32_e32 v83, v83
	v_cvt_f32_i32_e32 v82, v82
	v_cvt_f32_i32_e32 v67, v67
	v_cvt_f32_i32_e32 v66, v66
	v_cvt_f32_i32_e32 v63, v63
	v_cvt_f32_i32_e32 v62, v62
	v_cvt_f32_i32_e32 v29, v29
	v_cvt_f32_i32_e32 v28, v28
	v_cvt_f32_i32_e32 v25, v25
	v_cvt_f32_i32_e32 v24, v24
	v_cvt_f32_i32_e32 v19, v19
	v_cvt_f32_i32_e32 v18, v18
	v_cvt_f32_i32_e32 v15, v15
	v_cvt_f32_i32_e32 v14, v14
	v_cvt_f32_i32_e32 v75, v75
	v_cvt_f32_i32_e32 v74, v74
	v_cvt_f32_i32_e32 v23, v23
	v_cvt_f32_i32_e32 v22, v22
	v_cvt_f32_i32_e32 v21, v21
	v_cvt_f32_i32_e32 v20, v20
	v_cvt_f32_i32_e32 v71, v71
	v_cvt_f32_i32_e32 v70, v70
	s_waitcnt vmcnt(5)
	v_pk_mul_f32 v[224:225], v[112:113], v[146:147] op_sel_hi:[0,1]
	v_cvt_f32_i32_e32 v147, v157
	v_cvt_f32_i32_e32 v146, v156
	v_cvt_f32_i32_e32 v157, v159
	v_cvt_f32_i32_e32 v156, v158
	s_waitcnt vmcnt(4)
	v_mov_b32_e32 v158, v107
	v_add_u32_e32 v145, 0xb010, v208
	v_pk_mul_f32 v[220:221], v[112:113], v[160:161] op_sel_hi:[0,1]
	v_pk_mul_f32 v[218:219], v[158:159], v[156:157] op_sel_hi:[0,1]
	v_pk_mul_f32 v[222:223], v[158:159], v[146:147] op_sel_hi:[0,1]
	global_load_dwordx4 v[160:163], v[164:165], off offset:16
	global_load_dwordx4 v[156:159], v145, s[22:23]
	v_add_u32_e32 v145, 0x16010, v208
	global_load_dwordx4 v[164:167], v145, s[22:23]
	global_load_dwordx4 v[168:171], v[180:181], off offset:16
	s_waitcnt vmcnt(4)
	v_mov_b32_dpp v120, v222 row_shr:1 row_mask:0xf bank_mask:0xf
	v_mov_b32_dpp v124, v224 row_shl:1 row_mask:0xf bank_mask:0xf
	v_mov_b32_dpp v121, v223 row_shr:1 row_mask:0xf bank_mask:0xf
	v_mov_b32_dpp v125, v225 row_shl:1 row_mask:0xf bank_mask:0xf
	v_mov_b32_dpp v122, v218 row_shr:1 row_mask:0xf bank_mask:0xf
	v_mov_b32_dpp v126, v220 row_shl:1 row_mask:0xf bank_mask:0xf
	v_mov_b32_dpp v123, v219 row_shr:1 row_mask:0xf bank_mask:0xf
	v_mov_b32_dpp v127, v221 row_shl:1 row_mask:0xf bank_mask:0xf
	s_cmp_lg_u64 s[44:45], 0
	s_cbranch_scc1 .Lzs_2
	v_mov_b32_e32 v145, 0
	v_mov_b32_e32 v146, 0
	v_mov_b32_e32 v147, 0

;     __device__ bool next(int i, Unit& u) const { return S.next(i, u); }
;     __device__ bool next(int i, Unit& u) const { const int L = i * G + c; if (L >= 3 * 44) return false; u.pm = L % 3; u.pn = L / 3; u.g = 0; u.part = 0; u.keep = 0; return true; }
;     __device__ __forceinline__ void operator()(Acc& acc, const Unit& u, int wr, int wc, int fr, int fq, LAS unsigned char* lds, int tid) const {
;     ...
;         for (int bj = 0; bj < 2; ++bj) {
;             const unsigned colp = u.pn * 256 + bj * 128 + wc * 32 + 8 * fq;
;             const unsigned coll = bj * FF + u.pn * 128 + wc * 32 + 8 * fq;
; #pragma unroll
;             for (int n = 0; n < 2; ++n) {
;                 f32x4 c0 = ldf4(cw, coll + 4u * n), c1 = ldf4(cw, (unsigned)FF2 + coll + 4u * n), c2 = ldf4(cw, 2u * FF2 + coll + 4u * n);
;                 if constexpr (I8) { const f32x4 swv = ldf4(sw, colp + 4u * n); c0 = c0 * swv; c1 = c1 * swv; c2 = c2 * swv; }
;                 f32x4 hl = {0.f, 0.f, 0.f, 0.f}, hr = {0.f, 0.f, 0.f, 0.f};
;                 if (fr == 0 && lvalid) hl = ldf4(HALO, (2u * bk) * (unsigned)FF2 + colp + 4u * n);
;                 if (fr == 15 && rvalid) hr = ldf4(HALO, (2u * bk + 1u) * (unsigned)FF2 + colp + 4u * n);
; #pragma unroll
;                 for (int e = 0; e < 4; ++e) {
;                     const float prev = dpp_shr1(hl[e], acc[1][bj][3][n][e]);
;                     const float next = dpp_shl1(hr[e], acc[0][bj][0][n][e]);
.LBB0_1076:
	s_or_b64 exec, exec, s[60:61]
	v_mov_b32_e32 v226, v107
	v_mov_b32_e32 v227, v107
	v_pk_mul_f32 v[234:235], v[226:227], v[148:149]
	v_add_u32_e32 v149, 0x5800, v208
	global_load_dwordx4 v[188:191], v149, s[22:23]
	v_add_u32_e32 v149, 0x10800, v208
	v_or_b32_e32 v148, 0x80, v177
	global_load_dwordx4 v[196:199], v149, s[22:23]
	v_add_u32_e32 v149, 0x1b800, v208
	global_load_dwordx4 v[192:195], v149, s[22:23]
	v_lshlrev_b32_e32 v149, 2, v148
	global_load_dwordx4 v[200:203], v149, s[28:29]
	v_mov_b32_e32 v228, v112
	v_mov_b32_e32 v229, v112
	v_mov_b32_e32 v178, v112
	v_mov_b32_e32 v179, v112
	v_pk_mul_f32 v[236:237], v[228:229], v[152:153]
	v_mov_b32_e32 v152, v107
	v_mov_b32_e32 v153, v107
	v_pk_mul_f32 v[232:233], v[178:179], v[154:155]
	v_pk_mul_f32 v[230:231], v[152:153], v[150:151]
	s_waitcnt vmcnt(4)
	v_mov_b32_dpp v144, v234 row_shr:1 row_mask:0xf bank_mask:0xf
	v_mov_b32_dpp v172, v236 row_shl:1 row_mask:0xf bank_mask:0xf
	v_mov_b32_dpp v145, v235 row_shr:1 row_mask:0xf bank_mask:0xf
	v_mov_b32_dpp v173, v237 row_shl:1 row_mask:0xf bank_mask:0xf
	v_mov_b32_dpp v146, v230 row_shr:1 row_mask:0xf bank_mask:0xf
	v_mov_b32_dpp v174, v232 row_shl:1 row_mask:0xf bank_mask:0xf
	v_mov_b32_dpp v147, v231 row_shr:1 row_mask:0xf bank_mask:0xf
	v_mov_b32_dpp v175, v233 row_shl:1 row_mask:0xf bank_mask:0xf
	v_add_u32_e32 v215, s1, v148
	s_cmp_lg_u64 s[44:45], 0
	s_cbranch_scc1 .Lzs_4
	v_mov_b32_e32 v177, 0
	v_mov_b32_e32 v178, 0
	v_mov_b32_e32 v179, 0

;     __device__ bool next(int i, Unit& u) const { return S.next(i, u); }
;     __device__ bool next(int i, Unit& u) const { const int L = i * G + c; if (L >= 3 * 44) return false; u.pm = L % 3; u.pn = L / 3; u.g = 0; u.part = 0; u.keep = 0; return true; }
;     __device__ __forceinline__ void operator()(Acc& acc, const Unit& u, int wr, int wc, int fr, int fq, LAS unsigned char* lds, int tid) const {
;     ...
;         for (int bj = 0; bj < 2; ++bj) {
;             const unsigned colp = u.pn * 256 + bj * 128 + wc * 32 + 8 * fq;
;             const unsigned coll = bj * FF + u.pn * 128 + wc * 32 + 8 * fq;
; #pragma unroll
;             for (int n = 0; n < 2; ++n) {
;                 f32x4 c0 = ldf4(cw, coll + 4u * n), c1 = ldf4(cw, (unsigned)FF2 + coll + 4u * n), c2 = ldf4(cw, 2u * FF2 + coll + 4u * n);
;                 if constexpr (I8) { const f32x4 swv = ldf4(sw, colp + 4u * n); c0 = c0 * swv; c1 = c1 * swv; c2 = c2 * swv; }
;                 f32x4 hl = {0.f, 0.f, 0.f, 0.f}, hr = {0.f, 0.f, 0.f, 0.f};
;                 if (fr == 0 && lvalid) hl = ldf4(HALO, (2u * bk) * (unsigned)FF2 + colp + 4u * n);
;                 if (fr == 15 && rvalid) hr = ldf4(HALO, (2u * bk + 1u) * (unsigned)FF2 + colp + 4u * n);
; #pragma unroll
;                 for (int e = 0; e < 4; ++e) {
;                     const float prev = dpp_shr1(hl[e], acc[1][bj][3][n][e]);
;                     const float next = dpp_shl1(hr[e], acc[0][bj][0][n][e]);
.LBB0_1080:
	s_or_b64 exec, exec, s[60:61]
	v_mov_b32_e32 v150, v112
	v_mov_b32_e32 v151, v112
	v_pk_mul_f32 v[244:245], v[228:229], v[116:117]
	v_mov_b32_e32 v116, v107
	v_mov_b32_e32 v117, v107
	v_pk_mul_f32 v[242:243], v[226:227], v[108:109]
	v_add_u32_e32 v108, 0x5810, v208
	v_pk_mul_f32 v[240:241], v[150:151], v[118:119]
	v_pk_mul_f32 v[238:239], v[116:117], v[110:111]
	global_load_dwordx4 v[116:119], v108, s[22:23]
	v_add_u32_e32 v108, 0x10810, v208
	global_load_dwordx4 v[184:187], v108, s[22:23]
	v_add_u32_e32 v108, 0x1b810, v208
	global_load_dwordx4 v[152:155], v108, s[22:23]
	s_nop 0
	global_load_dwordx4 v[180:183], v[180:181], off offset:528
	s_waitcnt vmcnt(4)
	v_mov_b32_dpp v176, v242 row_shr:1 row_mask:0xf bank_mask:0xf
	v_mov_b32_dpp v204, v244 row_shl:1 row_mask:0xf bank_mask:0xf
	v_mov_b32_dpp v177, v243 row_shr:1 row_mask:0xf bank_mask:0xf
	v_mov_b32_dpp v205, v245 row_shl:1 row_mask:0xf bank_mask:0xf
	v_mov_b32_dpp v178, v238 row_shr:1 row_mask:0xf bank_mask:0xf
	v_mov_b32_dpp v206, v240 row_shl:1 row_mask:0xf bank_mask:0xf
	v_mov_b32_dpp v179, v239 row_shr:1 row_mask:0xf bank_mask:0xf
	v_mov_b32_dpp v207, v241 row_shl:1 row_mask:0xf bank_mask:0xf
	s_cmp_lg_u64 s[44:45], 0
	s_cbranch_scc1 .Lzs_6
	v_mov_b32_e32 v149, 0
	v_mov_b32_e32 v150, 0
	v_mov_b32_e32 v151, 0

;     __device__ __forceinline__ void operator()(Acc& acc, const Unit& u, int wr, int wc, int fr, int fq, LAS unsigned char* lds, int tid) const {
;     ...
;         if constexpr (I8) {
; #pragma unroll
;             for (int ai = 0; ai < 2; ++ai) { const f32x4 sa = ldf4(sx, tok0 + tl0 + 4u * ai);
; #pragma unroll
;                 for (int m = 0; m < 4; ++m)
; #pragma unroll
;                     for (int bj = 0; bj < 2; ++bj)
; #pragma unroll
;                         for (int n = 0; n < 2; ++n) { const pg8::i32x4 iv = __builtin_bit_cast(pg8::i32x4, acc[ai][bj][m][n]); acc[ai][bj][m][n] = __builtin_convertvector(iv, f32x4) * sa[m]; }
;                 asm volatile("" ::: "memory"); }
;         }
;         const unsigned bk = 2 * u.pm + wr;
;         const bool lvalid = (bk & 15) != 0, rvalid = (bk & 15) != 15;
; #pragma unroll
;         for (int bj = 0; bj < 2; ++bj) {
;             const unsigned colp = u.pn * 256 + bj * 128 + wc * 32 + 8 * fq;
;             const unsigned coll = bj * FF + u.pn * 128 + wc * 32 + 8 * fq;
; #pragma unroll
;             for (int n = 0; n < 2; ++n) {
;                 f32x4 c0 = ldf4(cw, coll + 4u * n), c1 = ldf4(cw, (unsigned)FF2 + coll + 4u * n), c2 = ldf4(cw, 2u * FF2 + coll + 4u * n);
;                 if constexpr (I8) { const f32x4 swv = ldf4(sw, colp + 4u * n); c0 = c0 * swv; c1 = c1 * swv; c2 = c2 * swv; }
;                 f32x4 hl = {0.f, 0.f, 0.f, 0.f}, hr = {0.f, 0.f, 0.f, 0.f};
;                 if (fr == 0 && lvalid) hl = ldf4(HALO, (2u * bk) * (unsigned)FF2 + colp + 4u * n);
;                 if (fr == 15 && rvalid) hr = ldf4(HALO, (2u * bk + 1u) * (unsigned)FF2 + colp + 4u * n);
; #pragma unroll
;                 for (int e = 0; e < 4; ++e) {
;                     const float prev = dpp_shr1(hl[e], acc[1][bj][3][n][e]);
;                     const float next = dpp_shl1(hr[e], acc[0][bj][0][n][e]);
;                     float left = prev;
; #pragma unroll
;                     for (int j = 0; j < 8; ++j) {
;                         const float cur = acc[j >> 2][bj][j & 3][n][e];
;                         const float nx = (j < 7) ? acc[(j + 1) >> 2][bj][(j + 1) & 3][n][e] : next;
;                         acc[j >> 2][bj][j & 3][n][e] = c0[e] * left + c1[e] * cur + c2[e] * nx;
;                         left = cur;
;                     }
;                 }
;                 asm volatile("" ::: "memory");
;             }
.LBB0_1084:
	s_or_b64 exec, exec, s[44:45]
	v_pk_mul_f32 v[136:137], v[136:137], v[132:133]
	v_pk_mul_f32 v[140:141], v[140:141], v[132:133]
	v_pk_mul_f32 v[120:121], v[136:137], v[120:121]
	v_pk_mul_f32 v[52:53], v[112:113], v[52:53] op_sel:[1,0]
	v_pk_mul_f32 v[138:139], v[138:139], v[134:135]
	v_pk_mul_f32 v[142:143], v[142:143], v[134:135]
	v_pk_mul_f32 v[134:135], v[130:131], v[134:135]
	v_pk_mul_f32 v[130:131], v[128:129], v[132:133]
	v_pk_fma_f32 v[120:121], v[224:225], v[140:141], v[120:121]
	v_pk_fma_f32 v[132:133], v[52:53], v[130:131], v[120:121]
	v_pk_mul_f32 v[120:121], v[52:53], v[140:141]
	v_pk_mul_f32 v[48:49], v[114:115], v[48:49] op_sel_hi:[0,1]
	v_pk_fma_f32 v[120:121], v[224:225], v[136:137], v[120:121]
	v_mov_b32_e32 v208, v115
	v_pk_fma_f32 v[128:129], v[48:49], v[130:131], v[120:121]
	v_pk_mul_f32 v[120:121], v[48:49], v[140:141]
	v_pk_mul_f32 v[44:45], v[208:209], v[44:45] op_sel_hi:[0,1]
	v_pk_fma_f32 v[52:53], v[52:53], v[136:137], v[120:121]
	v_pk_mul_f32 v[40:41], v[104:105], v[40:41] op_sel_hi:[0,1]
	v_pk_fma_f32 v[120:121], v[44:45], v[130:131], v[52:53]
	v_pk_mul_f32 v[52:53], v[44:45], v[140:141]
	v_pk_mul_f32 v[36:37], v[104:105], v[36:37] op_sel:[1,0]
	v_pk_fma_f32 v[48:49], v[48:49], v[136:137], v[52:53]
	v_pk_mul_f32 v[52:53], v[40:41], v[140:141]
	v_pk_mul_f32 v[32:33], v[106:107], v[32:33] op_sel_hi:[0,1]
	v_pk_fma_f32 v[44:45], v[44:45], v[136:137], v[52:53]
	v_pk_mul_f32 v[52:53], v[36:37], v[140:141]
	v_pk_fma_f32 v[48:49], v[40:41], v[130:131], v[48:49]
	v_pk_fma_f32 v[40:41], v[40:41], v[136:137], v[52:53]
	v_pk_mul_f32 v[52:53], v[32:33], v[140:141]
	v_pk_fma_f32 v[44:45], v[36:37], v[130:131], v[44:45]
	v_pk_fma_f32 v[36:37], v[36:37], v[136:137], v[52:53]
	v_pk_mul_f32 v[52:53], v[138:139], v[122:123]
	v_pk_mul_f32 v[54:55], v[112:113], v[54:55] op_sel:[1,0]
	v_pk_fma_f32 v[52:53], v[220:221], v[142:143], v[52:53]
	v_pk_fma_f32 v[40:41], v[32:33], v[130:131], v[40:41]
	v_pk_mul_f32 v[32:33], v[32:33], v[136:137]
	v_pk_fma_f32 v[136:137], v[54:55], v[134:135], v[52:53]
	v_pk_mul_f32 v[52:53], v[54:55], v[142:143]
	v_pk_mul_f32 v[50:51], v[114:115], v[50:51] op_sel_hi:[0,1]
	v_pk_fma_f32 v[32:33], v[222:223], v[140:141], v[32:33]
	v_pk_fma_f32 v[52:53], v[220:221], v[138:139], v[52:53]
	v_pk_fma_f32 v[36:37], v[222:223], v[130:131], v[36:37]
	v_pk_fma_f32 v[32:33], v[130:131], v[124:125], v[32:33]
	v_pk_fma_f32 v[130:131], v[50:51], v[134:135], v[52:53]
	v_pk_mul_f32 v[52:53], v[50:51], v[142:143]
	v_pk_mul_f32 v[46:47], v[208:209], v[46:47] op_sel_hi:[0,1]
	v_pk_fma_f32 v[52:53], v[54:55], v[138:139], v[52:53]
	v_pk_mul_f32 v[42:43], v[104:105], v[42:43] op_sel_hi:[0,1]
	v_pk_fma_f32 v[122:123], v[46:47], v[134:135], v[52:53]
	v_pk_mul_f32 v[52:53], v[46:47], v[142:143]
	v_pk_mul_f32 v[38:39], v[104:105], v[38:39] op_sel:[1,0]
	v_pk_fma_f32 v[50:51], v[50:51], v[138:139], v[52:53]
	v_pk_mul_f32 v[52:53], v[42:43], v[142:143]
	v_pk_mul_f32 v[214:215], v[190:191], v[202:203]
	v_pk_mul_f32 v[190:191], v[188:189], v[200:201]
	v_pk_fma_f32 v[46:47], v[46:47], v[138:139], v[52:53]
	v_pk_mul_f32 v[52:53], v[38:39], v[142:143]
	v_pk_mul_f32 v[124:125], v[112:113], v[26:27] op_sel:[1,0]
	v_pk_mul_f32 v[26:27], v[104:105], v[12:13] op_sel_hi:[0,1]
	v_cvt_f32_i32_e32 v13, v9
	v_cvt_f32_i32_e32 v12, v8
	v_pk_mul_f32 v[196:197], v[196:197], v[200:201]
	v_pk_mul_f32 v[176:177], v[190:191], v[176:177]
	v_pk_mul_f32 v[34:35], v[106:107], v[34:35] op_sel_hi:[0,1]
	v_pk_fma_f32 v[50:51], v[42:43], v[134:135], v[50:51]
	v_pk_fma_f32 v[42:43], v[42:43], v[138:139], v[52:53]
	v_pk_mul_f32 v[100:101], v[112:113], v[100:101] op_sel:[1,0]
	v_pk_mul_f32 v[96:97], v[114:115], v[96:97] op_sel_hi:[0,1]
	v_pk_mul_f32 v[192:193], v[192:193], v[200:201]
	v_pk_fma_f32 v[176:177], v[244:245], v[196:197], v[176:177]
	v_pk_fma_f32 v[42:43], v[34:35], v[134:135], v[42:43]
	v_pk_mul_f32 v[52:53], v[34:35], v[142:143]
	v_pk_mul_f32 v[34:35], v[34:35], v[138:139]
	v_pk_mul_f32 v[92:93], v[208:209], v[92:93] op_sel_hi:[0,1]
	v_pk_fma_f32 v[188:189], v[100:101], v[192:193], v[176:177]
	v_pk_mul_f32 v[176:177], v[100:101], v[196:197]
	v_pk_mul_f32 v[200:201], v[96:97], v[196:197]
	v_pk_fma_f32 v[46:47], v[38:39], v[134:135], v[46:47]
	v_pk_fma_f32 v[38:39], v[38:39], v[138:139], v[52:53]
	v_pk_fma_f32 v[34:35], v[218:219], v[142:143], v[34:35]
	v_mov_b32_e32 v52, v112
	v_mov_b32_e32 v53, v112
	v_pk_mul_f32 v[8:9], v[104:105], v[10:11] op_sel:[1,0]
	v_cvt_f32_i32_e32 v11, v5
	v_cvt_f32_i32_e32 v10, v4
	v_pk_mul_f32 v[88:89], v[104:105], v[88:89] op_sel_hi:[0,1]
	v_pk_fma_f32 v[176:177], v[244:245], v[190:191], v[176:177]
	v_pk_fma_f32 v[100:101], v[100:101], v[190:191], v[200:201]
	v_pk_mul_f32 v[200:201], v[92:93], v[196:197]
	v_pk_fma_f32 v[34:35], v[134:135], v[126:127], v[34:35]
	v_pk_mul_f32 v[126:127], v[52:53], v[30:31]
	v_pk_mul_f32 v[30:31], v[208:209], v[16:17] op_sel_hi:[0,1]
	v_pk_mul_f32 v[16:17], v[104:105], v[12:13] op_sel:[1,0]
	v_cvt_f32_i32_e32 v13, v3
	v_cvt_f32_i32_e32 v12, v2
	v_pk_mul_f32 v[84:85], v[104:105], v[84:85] op_sel:[1,0]
	v_pk_fma_f32 v[176:177], v[96:97], v[192:193], v[176:177]
	v_pk_fma_f32 v[96:97], v[96:97], v[190:191], v[200:201]
	v_pk_mul_f32 v[200:201], v[88:89], v[196:197]
	v_pk_fma_f32 v[100:101], v[92:93], v[192:193], v[100:101]
	v_pk_fma_f32 v[92:93], v[92:93], v[190:191], v[200:201]
	v_pk_mul_f32 v[200:201], v[84:85], v[196:197]
	v_pk_mul_f32 v[78:79], v[106:107], v[78:79] op_sel_hi:[0,1]
	v_pk_mul_f32 v[76:77], v[106:107], v[76:77] op_sel_hi:[0,1]
	v_pk_fma_f32 v[96:97], v[88:89], v[192:193], v[96:97]
	v_pk_fma_f32 v[88:89], v[88:89], v[190:191], v[200:201]
;     __device__ __forceinline__ void operator()(Acc& acc, const Unit& u, int wr, int wc, int fr, int fq, LAS unsigned char* lds, int tid) const {
;     ...
;                         for (int n = 0; n < 2; ++n) { const pg8::i32x4 iv = __builtin_bit_cast(pg8::i32x4, acc[ai][bj][m][n]); acc[ai][bj][m][n] = __builtin_convertvector(iv, f32x4) * sa[m]; }
;                 asm volatile("" ::: "memory"); }
;         }
;         const unsigned bk = 2 * u.pm + wr;
;         const bool lvalid = (bk & 15) != 0, rvalid = (bk & 15) != 15;
; #pragma unroll
;         for (int bj = 0; bj < 2; ++bj) {
;             const unsigned colp = u.pn * 256 + bj * 128 + wc * 32 + 8 * fq;
;             const unsigned coll = bj * FF + u.pn * 128 + wc * 32 + 8 * fq;
; #pragma unroll
;             for (int n = 0; n < 2; ++n) {
;                 f32x4 c0 = ldf4(cw, coll + 4u * n), c1 = ldf4(cw, (unsigned)FF2 + coll + 4u * n), c2 = ldf4(cw, 2u * FF2 + coll + 4u * n);
;                 if constexpr (I8) { const f32x4 swv = ldf4(sw, colp + 4u * n); c0 = c0 * swv; c1 = c1 * swv; c2 = c2 * swv; }
;                 f32x4 hl = {0.f, 0.f, 0.f, 0.f}, hr = {0.f, 0.f, 0.f, 0.f};
;                 if (fr == 0 && lvalid) hl = ldf4(HALO, (2u * bk) * (unsigned)FF2 + colp + 4u * n);
;                 if (fr == 15 && rvalid) hr = ldf4(HALO, (2u * bk + 1u) * (unsigned)FF2 + colp + 4u * n);
; #pragma unroll
;                 for (int e = 0; e < 4; ++e) {
;                     const float prev = dpp_shr1(hl[e], acc[1][bj][3][n][e]);
;                     const float next = dpp_shl1(hr[e], acc[0][bj][0][n][e]);
;                     float left = prev;
; #pragma unroll
;                     for (int j = 0; j < 8; ++j) {
;                         const float cur = acc[j >> 2][bj][j & 3][n][e];
;                         const float nx = (j < 7) ? acc[(j + 1) >> 2][bj][(j + 1) & 3][n][e] : next;
;                         acc[j >> 2][bj][j & 3][n][e] = c0[e] * left + c1[e] * cur + c2[e] * nx;
;                         left = cur;
;                     }
;                 }
;                 asm volatile("" ::: "memory");
;             }
;         }
;         const unsigned colo = u.pn * 128 + wc * 32 + 8 * fq;
; #pragma unroll
;         for (int ai = 0; ai < 2; ++ai)
; #pragma unroll
;             for (int m = 0; m < 4; ++m) {
;                 f32x4 a[2];
; #pragma unroll
;                 for (int n = 0; n < 2; ++n)
	v_pk_mul_f32 v[58:59], v[106:107], v[58:59] op_sel_hi:[0,1]
	v_pk_mul_f32 v[56:57], v[106:107], v[56:57] op_sel_hi:[0,1]
	v_pk_mul_f32 v[4:5], v[106:107], v[6:7] op_sel_hi:[0,1]
	v_pk_mul_f32 v[2:3], v[106:107], v[10:11] op_sel_hi:[0,1]
	v_mov_b32_e32 v106, v107
	v_pk_mul_f32 v[10:11], v[132:133], s[100:101] op_sel_hi:[1,0]
	v_pk_mul_f32 v[198:199], v[198:199], v[202:203]
	v_pk_fma_f32 v[88:89], v[76:77], v[192:193], v[88:89]
	v_pk_mul_f32 v[200:201], v[76:77], v[196:197]
	v_pk_mul_f32 v[76:77], v[76:77], v[190:191]
	v_pk_mul_f32 v[178:179], v[214:215], v[178:179]
	v_cvt_f32_i32_e32 v7, v1
	v_cvt_f32_i32_e32 v6, v0
	v_pk_mul_f32 v[0:1], v[106:107], v[12:13]
	v_exp_f32_e32 v10, v10
	v_exp_f32_e32 v11, v11
	v_pk_mul_f32 v[12:13], v[136:137], s[100:101] op_sel_hi:[1,0]
	v_pk_mul_f32 v[102:103], v[112:113], v[102:103] op_sel:[1,0]
	v_pk_mul_f32 v[98:99], v[114:115], v[98:99] op_sel_hi:[0,1]
	v_pk_mul_f32 v[194:195], v[194:195], v[202:203]
	v_pk_fma_f32 v[92:93], v[84:85], v[192:193], v[92:93]
	v_pk_fma_f32 v[84:85], v[84:85], v[190:191], v[200:201]
	v_pk_fma_f32 v[76:77], v[242:243], v[196:197], v[76:77]
	v_pk_fma_f32 v[178:179], v[240:241], v[198:199], v[178:179]
	v_exp_f32_e32 v12, v12
	v_exp_f32_e32 v13, v13
	v_pk_mul_f32 v[94:95], v[208:209], v[94:95] op_sel_hi:[0,1]
	v_pk_fma_f32 v[84:85], v[242:243], v[192:193], v[84:85]
	v_pk_fma_f32 v[76:77], v[192:193], v[204:205], v[76:77]
	v_pk_fma_f32 v[190:191], v[102:103], v[194:195], v[178:179]
	v_pk_mul_f32 v[178:179], v[102:103], v[198:199]
	v_pk_mul_f32 v[192:193], v[98:99], v[198:199]
	v_pk_mul_f32 v[90:91], v[104:105], v[90:91] op_sel_hi:[0,1]
	v_pk_fma_f32 v[178:179], v[240:241], v[214:215], v[178:179]
	v_pk_fma_f32 v[102:103], v[102:103], v[214:215], v[192:193]
	v_pk_mul_f32 v[192:193], v[94:95], v[198:199]
	v_pk_mul_f32 v[86:87], v[104:105], v[86:87] op_sel:[1,0]
	v_pk_fma_f32 v[178:179], v[98:99], v[194:195], v[178:179]
	v_pk_fma_f32 v[98:99], v[98:99], v[214:215], v[192:193]
	v_pk_mul_f32 v[192:193], v[90:91], v[198:199]
	v_pk_add_f32 v[10:11], v[10:11], 1.0 op_sel_hi:[1,0]
	v_pk_fma_f32 v[102:103], v[94:95], v[194:195], v[102:103]
	v_pk_fma_f32 v[94:95], v[94:95], v[214:215], v[192:193]
	v_pk_mul_f32 v[192:193], v[86:87], v[198:199]
	v_rcp_f32_e32 v10, v10
	v_rcp_f32_e32 v11, v11
	v_pk_add_f32 v[12:13], v[12:13], 1.0 op_sel_hi:[1,0]
	v_pk_fma_f32 v[98:99], v[90:91], v[194:195], v[98:99]
	v_pk_fma_f32 v[90:91], v[90:91], v[214:215], v[192:193]
	v_pk_mul_f32 v[192:193], v[78:79], v[198:199]
	v_pk_mul_f32 v[160:161], v[160:161], v[168:169]
	v_rcp_f32_e32 v12, v12
	v_rcp_f32_e32 v13, v13
	v_pk_fma_f32 v[94:95], v[86:87], v[194:195], v[94:95]
	v_pk_fma_f32 v[86:87], v[86:87], v[214:215], v[192:193]
	v_pk_mul_f32 v[192:193], v[158:159], v[170:171]
	v_pk_mul_f32 v[158:159], v[156:157], v[168:169]
	v_pk_mul_f32 v[144:145], v[160:161], v[144:145]
	v_pk_mul_f32 v[80:81], v[112:113], v[80:81] op_sel:[1,0]
	v_pk_mul_f32 v[72:73], v[114:115], v[72:73] op_sel_hi:[0,1]
	v_pk_mul_f32 v[164:165], v[164:165], v[168:169]
	v_pk_fma_f32 v[144:145], v[236:237], v[158:159], v[144:145]
	v_pk_mul_f32 v[68:69], v[208:209], v[68:69] op_sel_hi:[0,1]
	v_pk_fma_f32 v[156:157], v[80:81], v[164:165], v[144:145]
	v_pk_mul_f32 v[144:145], v[80:81], v[158:159]
	v_pk_mul_f32 v[168:169], v[72:73], v[158:159]
	v_pk_mul_f32 v[10:11], v[132:133], v[10:11]
	v_pk_mul_f32 v[64:65], v[104:105], v[64:65] op_sel_hi:[0,1]
	v_pk_fma_f32 v[144:145], v[236:237], v[160:161], v[144:145]
	v_pk_fma_f32 v[80:81], v[80:81], v[160:161], v[168:169]
	v_pk_mul_f32 v[168:169], v[68:69], v[158:159]
	v_pk_mul_f32 v[106:107], v[10:11], v[188:189]
	v_pk_mul_f32 v[10:11], v[136:137], v[12:13]
	v_mul_f32_e32 v12, 0xbfb8aa3b, v156
	v_pk_mul_f32 v[60:61], v[104:105], v[60:61] op_sel:[1,0]
	v_pk_fma_f32 v[144:145], v[72:73], v[164:165], v[144:145]
	v_pk_fma_f32 v[72:73], v[72:73], v[160:161], v[168:169]
	v_pk_mul_f32 v[168:169], v[64:65], v[158:159]
	v_exp_f32_e32 v12, v12
	v_mul_f32_e32 v13, 0xbfb8aa3b, v157
	v_pk_mul_f32 v[162:163], v[162:163], v[170:171]
	v_pk_fma_f32 v[80:81], v[68:69], v[164:165], v[80:81]
	v_pk_fma_f32 v[68:69], v[68:69], v[160:161], v[168:169]
	v_pk_mul_f32 v[168:169], v[60:61], v[158:159]
	v_exp_f32_e32 v13, v13
	v_pk_fma_f32 v[72:73], v[64:65], v[164:165], v[72:73]
	v_pk_fma_f32 v[64:65], v[64:65], v[160:161], v[168:169]
	v_pk_mul_f32 v[146:147], v[162:163], v[146:147]
	v_pk_mul_f32 v[82:83], v[112:113], v[82:83] op_sel:[1,0]
	v_pk_mul_f32 v[166:167], v[166:167], v[170:171]
	v_pk_fma_f32 v[64:65], v[56:57], v[164:165], v[64:65]
	v_pk_mul_f32 v[168:169], v[56:57], v[158:159]
	v_pk_mul_f32 v[56:57], v[56:57], v[160:161]
	v_pk_fma_f32 v[146:147], v[232:233], v[192:193], v[146:147]
	v_pk_fma_f32 v[56:57], v[234:235], v[158:159], v[56:57]
	v_pk_fma_f32 v[158:159], v[82:83], v[166:167], v[146:147]
	v_pk_mul_f32 v[132:133], v[10:11], v[190:191]
	v_add_f32_e32 v10, 1.0, v12
	v_pk_mul_f32 v[66:67], v[104:105], v[66:67] op_sel_hi:[0,1]
	v_pk_mul_f32 v[62:63], v[104:105], v[62:63] op_sel:[1,0]
	v_pk_fma_f32 v[38:39], v[218:219], v[134:135], v[38:39]
	v_pk_mul_f32 v[134:135], v[228:229], v[28:29]
	v_pk_mul_f32 v[112:113], v[112:113], v[24:25] op_sel:[1,0]
	v_pk_mul_f32 v[28:29], v[208:209], v[18:19] op_sel_hi:[0,1]
	v_pk_mul_f32 v[24:25], v[104:105], v[14:15] op_sel_hi:[0,1]
	v_rcp_f32_e32 v104, v10
	v_add_f32_e32 v10, 1.0, v13
	s_waitcnt vmcnt(0)
;     __device__ bool next(int i, Unit& u) const {
;     __device__ __forceinline__ void operator()(Acc& acc, const Unit& u, int wr, int wc, int fr, int fq, LAS unsigned char* lds, int tid) const {
;     ...
;         for (int bj = 0; bj < 2; ++bj) {
;             const unsigned colp = u.pn * 256 + bj * 128 + wc * 32 + 8 * fq;
;             const unsigned coll = bj * FF + u.pn * 128 + wc * 32 + 8 * fq;
; #pragma unroll
;             for (int n = 0; n < 2; ++n) {
;                 f32x4 c0 = ldf4(cw, coll + 4u * n), c1 = ldf4(cw, (unsigned)FF2 + coll + 4u * n), c2 = ldf4(cw, 2u * FF2 + coll + 4u * n);
;                 if constexpr (I8) { const f32x4 swv = ldf4(sw, colp + 4u * n); c0 = c0 * swv; c1 = c1 * swv; c2 = c2 * swv; }
;                 f32x4 hl = {0.f, 0.f, 0.f, 0.f}, hr = {0.f, 0.f, 0.f, 0.f};
;                 if (fr == 0 && lvalid) hl = ldf4(HALO, (2u * bk) * (unsigned)FF2 + colp + 4u * n);
;                 if (fr == 15 && rvalid) hr = ldf4(HALO, (2u * bk + 1u) * (unsigned)FF2 + colp + 4u * n);
; #pragma unroll
;                 for (int e = 0; e < 4; ++e) {
;                     const float prev = dpp_shr1(hl[e], acc[1][bj][3][n][e]);
;                     const float next = dpp_shl1(hr[e], acc[0][bj][0][n][e]);
;                     float left = prev;
; #pragma unroll
;                     for (int j = 0; j < 8; ++j) {
;                         const float cur = acc[j >> 2][bj][j & 3][n][e];
;                         const float nx = (j < 7) ? acc[(j + 1) >> 2][bj][(j + 1) & 3][n][e] : next;
;                         acc[j >> 2][bj][j & 3][n][e] = c0[e] * left + c1[e] * cur + c2[e] * nx;
;                         left = cur;
;                     }
;                 }
;                 asm volatile("" ::: "memory");
;             }
;         }
;         const unsigned colo = u.pn * 128 + wc * 32 + 8 * fq;
; #pragma unroll
;         for (int ai = 0; ai < 2; ++ai)
; #pragma unroll
;             for (int m = 0; m < 4; ++m) {
;                 f32x4 a[2];
; #pragma unroll
;                 for (int n = 0; n < 2; ++n)
; #pragma unroll
;                     for (int e = 0; e < 4; ++e) a[n][e] = silu_f(acc[ai][0][m][n][e]) * acc[ai][1][m][n][e];
;                 store_h8_nt((h16*)((char*)ACT + (((tok0 + tl0 + 4u * ai + m) * (unsigned)FF + colo) << 1)), a[0], a[1]);
;                 asm volatile("" ::: "memory");
;             }
	v_pk_mul_f32 v[18:19], v[116:117], v[180:181]
	v_mul_f32_e32 v116, 0xbfb8aa3b, v158
	v_pk_mul_f32 v[6:7], v[226:227], v[6:7]
	v_rcp_f32_e32 v105, v10
	v_pk_mul_f32 v[10:11], v[118:119], v[182:183]
	v_exp_f32_e32 v118, v116
	v_mul_f32_e32 v116, 0xbfb8aa3b, v159
	v_mov_b32_dpp v148, v6 row_shr:1 row_mask:0xf bank_mask:0xf
	v_mov_b32_dpp v149, v7 row_shr:1 row_mask:0xf bank_mask:0xf
	v_exp_f32_e32 v119, v116
	v_pk_mul_f32 v[74:75], v[114:115], v[74:75] op_sel_hi:[0,1]
	v_pk_mul_f32 v[52:53], v[114:115], v[22:23] op_sel_hi:[0,1]
	v_pk_mul_f32 v[54:55], v[114:115], v[20:21] op_sel_hi:[0,1]
	v_pk_mul_f32 v[20:21], v[184:185], v[180:181]
	v_pk_mul_f32 v[114:115], v[18:19], v[148:149]
	v_pk_mul_f32 v[22:23], v[152:153], v[180:181]
	v_pk_fma_f32 v[114:115], v[134:135], v[20:21], v[114:115]
	v_pk_mul_f32 v[104:105], v[156:157], v[104:105]
	v_pk_fma_f32 v[114:115], v[112:113], v[22:23], v[114:115]
	v_mov_b32_dpp v150, v0 row_shr:1 row_mask:0xf bank_mask:0xf
	v_pk_mul_f32 v[116:117], v[104:105], v[114:115]
	v_pk_add_f32 v[104:105], v[118:119], 1.0 op_sel_hi:[1,0]
	v_rcp_f32_e32 v104, v104
	v_rcp_f32_e32 v105, v105
	v_mov_b32_dpp v151, v1 row_shr:1 row_mask:0xf bank_mask:0xf
	v_pk_mul_f32 v[12:13], v[186:187], v[182:183]
	v_pk_mul_f32 v[114:115], v[10:11], v[150:151]
	v_pk_mul_f32 v[14:15], v[154:155], v[182:183]
	v_pk_fma_f32 v[114:115], v[126:127], v[12:13], v[114:115]
	v_pk_mul_f32 v[104:105], v[158:159], v[104:105]
	v_pk_fma_f32 v[114:115], v[124:125], v[14:15], v[114:115]
	s_movk_i32 s0, 0x1600
	v_pk_mul_f32 v[118:119], v[104:105], v[114:115]
	v_mul_f32_e32 v105, 0xbfb8aa3b, v128
	v_cvt_pk_f16_f32 v114, v106, v107
	v_exp_f32_e32 v105, v105
	v_mul_f32_e32 v106, 0xbfb8aa3b, v129
	v_exp_f32_e32 v107, v106
	v_mul_lo_u32 v104, v212, s0
	s_mov_b32 s101, s36
	s_mov_b32 s94, s48
	s_mov_b32 s95, s50
	s_mov_b64 s[44:45], s[76:77]
	s_mov_b64 s[60:61], s[56:57]
	s_cmp_eq_u32 s101, 0
	s_cbranch_scc1 .Lh1065_skip
	s_add_i32 s93, s93, 1
	s_mul_i32 s0, s93, s71
	s_mul_hi_u32 s1, s93, s70
	s_add_i32 s1, s1, s0
	s_mul_i32 s0, s93, s70
	s_add_u32 s56, s0, s20
	s_addc_u32 s57, s1, s33
	s_cmp_lt_u32 s56, 0x2100
	s_cselect_b64 s[36:37], exec, 0
	s_cbranch_scc0 .Lh1065_pre
	s_lshr_b32 s1, s56, 3
	s_and_b32 s0, s56, 7
	s_mul_i32 s0, s0, 0x420
	s_add_i32 s0, s0, s1
	s_mul_hi_i32 s1, s0, 0x2e8ba2e9
	s_lshr_b32 s4, s1, 31
	s_ashr_i32 s1, s1, 5
	s_add_i32 s1, s1, s4
	s_lshl_b32 s4, s1, 2
	s_sub_i32 s5, 0xc0, s4
	s_mulk_i32 s1, 0xb0
	s_sub_i32 s0, s0, s1
	s_lshr_b32 s48, s0, 2
	s_and_b32 s0, s0, 3
	s_add_i32 s50, s4, s0

;     __device__ bool next(int i, Unit& u) const { return S.next(i, u); }
;     __device__ bool next(int i, Unit& u) const { const int L = i * G + c; if (L >= 3 * 44) return false; u.pm = L % 3; u.pn = L / 3; u.g = 0; u.part = 0; u.keep = 0; return true; }
; __device__ __forceinline__ float silu_f(float x) { return x * __builtin_amdgcn_rcpf(1.0f + __expf(-x)); }
;     __device__ __forceinline__ void operator()(Acc& acc, const Unit& u, int wr, int wc, int fr, int fq, LAS unsigned char* lds, int tid) const {
;     ...
;                 for (int e = 0; e < 4; ++e) {
;                     const float prev = dpp_shr1(hl[e], acc[1][bj][3][n][e]);
;                     const float next = dpp_shl1(hr[e], acc[0][bj][0][n][e]);
;                     float left = prev;
; #pragma unroll
;                     for (int j = 0; j < 8; ++j) {
;                         const float cur = acc[j >> 2][bj][j & 3][n][e];
;                         const float nx = (j < 7) ? acc[(j + 1) >> 2][bj][(j + 1) & 3][n][e] : next;
;                         acc[j >> 2][bj][j & 3][n][e] = c0[e] * left + c1[e] * cur + c2[e] * nx;
;                         left = cur;
;                     }
;                 }
;                 asm volatile("" ::: "memory");
;             }
;         }
;         const unsigned colo = u.pn * 128 + wc * 32 + 8 * fq;
; #pragma unroll
;         for (int ai = 0; ai < 2; ++ai)
; #pragma unroll
;             for (int m = 0; m < 4; ++m) {
;                 f32x4 a[2];
; #pragma unroll
;                 for (int n = 0; n < 2; ++n)
; #pragma unroll
;                     for (int e = 0; e < 4; ++e) a[n][e] = silu_f(acc[ai][0][m][n][e]) * acc[ai][1][m][n][e];
;                 store_h8_nt((h16*)((char*)ACT + (((tok0 + tl0 + 4u * ai + m) * (unsigned)FF + colo) << 1)), a[0], a[1]);
;                 asm volatile("" ::: "memory");
;             }
.Lh1065_skip:
	v_add_f32_e32 v105, 1.0, v105
	v_add_lshl_u32 v104, v104, v213, 1
	v_cvt_pk_f16_f32 v115, v132, v133
	v_cvt_pk_f16_f32 v116, v116, v117
	v_cvt_pk_f16_f32 v117, v118, v119
	v_rcp_f32_e32 v106, v105
	v_add_f32_e32 v105, 1.0, v107
	v_mul_f32_e32 v107, 0xbfb8aa3b, v130
	global_store_dwordx4 v104, v[114:117], s[14:15] nt
	v_pk_mul_f32 v[146:147], v[82:83], v[192:193]
	v_mov_b32_dpp v110, v126 row_shl:1 row_mask:0xf bank_mask:0xf
	v_exp_f32_e32 v114, v107
	v_mul_f32_e32 v107, 0xbfb8aa3b, v131
	v_exp_f32_e32 v115, v107
	v_rcp_f32_e32 v107, v105
	v_add_f32_e32 v105, 1.0, v114
	v_rcp_f32_e32 v114, v105
	v_add_f32_e32 v105, 1.0, v115
	v_rcp_f32_e32 v115, v105
	v_mul_f32_e32 v105, 0xbfb8aa3b, v144
	v_exp_f32_e32 v105, v105
	v_mul_f32_e32 v116, 0xbfb8aa3b, v145
	v_exp_f32_e32 v118, v116
	v_pk_fma_f32 v[146:147], v[232:233], v[162:163], v[146:147]
	v_pk_mul_f32 v[114:115], v[130:131], v[114:115]
	v_add_f32_e32 v105, 1.0, v105
	v_pk_fma_f32 v[146:147], v[74:75], v[166:167], v[146:147]
	v_pk_mul_f32 v[116:117], v[114:115], v[178:179]
	v_rcp_f32_e32 v114, v105
	v_add_f32_e32 v105, 1.0, v118
	v_rcp_f32_e32 v115, v105
	v_mul_f32_e32 v105, 0xbfb8aa3b, v146
	v_pk_mul_f32 v[106:107], v[128:129], v[106:107]
	v_exp_f32_e32 v105, v105
	v_mul_f32_e32 v128, 0xbfb8aa3b, v147
	v_exp_f32_e32 v128, v128
	v_pk_mul_f32 v[118:119], v[112:113], v[20:21]
	v_pk_mul_f32 v[114:115], v[144:145], v[114:115]
	v_pk_fma_f32 v[118:119], v[134:135], v[18:19], v[118:119]
	v_add_f32_e32 v105, 1.0, v105
	v_pk_fma_f32 v[118:119], v[54:55], v[22:23], v[118:119]
	v_mov_b32_dpp v111, v127 row_shl:1 row_mask:0xf bank_mask:0xf
	v_pk_mul_f32 v[118:119], v[114:115], v[118:119]
	v_rcp_f32_e32 v114, v105
	v_add_f32_e32 v105, 1.0, v128
	v_rcp_f32_e32 v115, v105
	v_pk_mul_f32 v[128:129], v[124:125], v[12:13]
	v_pk_mul_f32 v[106:107], v[106:107], v[176:177]
	v_pk_fma_f32 v[126:127], v[126:127], v[10:11], v[128:129]
	v_pk_mul_f32 v[114:115], v[146:147], v[114:115]
	v_pk_fma_f32 v[126:127], v[52:53], v[14:15], v[126:127]
	v_add_u32_e32 v105, 0x2c00, v104
	v_pk_mul_f32 v[126:127], v[114:115], v[126:127]
	v_cvt_pk_f16_f32 v114, v106, v107
	v_mul_f32_e32 v106, 0xbfb8aa3b, v120
	v_exp_f32_e32 v106, v106
	v_mul_f32_e32 v107, 0xbfb8aa3b, v121
	v_exp_f32_e32 v107, v107
	v_cvt_pk_f16_f32 v115, v116, v117
	v_cvt_pk_f16_f32 v116, v118, v119
	v_cvt_pk_f16_f32 v117, v126, v127
	global_store_dwordx4 v105, v[114:117], s[14:15] nt
	v_add_f32_e32 v105, 1.0, v106
	v_rcp_f32_e32 v106, v105
	v_add_f32_e32 v105, 1.0, v107
	v_mul_f32_e32 v107, 0xbfb8aa3b, v122
	v_exp_f32_e32 v114, v107
	v_mul_f32_e32 v107, 0xbfb8aa3b, v123
	v_exp_f32_e32 v115, v107
	v_rcp_f32_e32 v107, v105
	v_add_f32_e32 v105, 1.0, v114
	v_rcp_f32_e32 v114, v105
	v_add_f32_e32 v105, 1.0, v115
	v_rcp_f32_e32 v115, v105
	v_pk_mul_f32 v[106:107], v[120:121], v[106:107]
	v_mul_f32_e32 v105, 0xbfb8aa3b, v80
	v_pk_mul_f32 v[100:101], v[106:107], v[100:101]
	v_pk_mul_f32 v[106:107], v[122:123], v[114:115]
	v_exp_f32_e32 v105, v105
	v_mul_f32_e32 v114, 0xbfb8aa3b, v81
	v_exp_f32_e32 v114, v114
	v_add_f32_e32 v105, 1.0, v105
	v_pk_mul_f32 v[102:103], v[106:107], v[102:103]
	v_rcp_f32_e32 v106, v105
	v_add_f32_e32 v105, 1.0, v114
	v_rcp_f32_e32 v107, v105
	v_pk_fma_f32 v[68:69], v[60:61], v[164:165], v[68:69]
	v_pk_fma_f32 v[60:61], v[60:61], v[160:161], v[168:169]
	v_pk_mul_f32 v[160:161], v[74:75], v[192:193]
	v_pk_mul_f32 v[70:71], v[208:209], v[70:71] op_sel_hi:[0,1]
	v_pk_fma_f32 v[82:83], v[82:83], v[162:163], v[160:161]
	v_pk_mul_f32 v[114:115], v[54:55], v[20:21]
	v_pk_fma_f32 v[82:83], v[70:71], v[166:167], v[82:83]
	v_pk_mul_f32 v[80:81], v[80:81], v[106:107]
	v_mul_f32_e32 v105, 0xbfb8aa3b, v82
	v_mul_f32_e32 v106, 0xbfb8aa3b, v83
	v_pk_fma_f32 v[112:113], v[112:113], v[18:19], v[114:115]
	v_exp_f32_e32 v105, v105
	v_exp_f32_e32 v114, v106
	v_pk_fma_f32 v[112:113], v[30:31], v[22:23], v[112:113]
	v_pk_mul_f32 v[160:161], v[70:71], v[192:193]
	v_pk_mul_f32 v[106:107], v[80:81], v[112:113]
	v_add_f32_e32 v80, 1.0, v105
	v_add_f32_e32 v81, 1.0, v114
	v_rcp_f32_e32 v80, v80
	v_rcp_f32_e32 v81, v81
	v_pk_mul_f32 v[112:113], v[52:53], v[12:13]
	v_add_u32_e32 v105, 0x5800, v104
	v_pk_fma_f32 v[112:113], v[124:125], v[10:11], v[112:113]
	v_pk_mul_f32 v[80:81], v[82:83], v[80:81]
	v_pk_fma_f32 v[112:113], v[28:29], v[14:15], v[112:113]
	v_cvt_pk_f16_f32 v82, v106, v107
	v_pk_mul_f32 v[112:113], v[80:81], v[112:113]
	v_cvt_pk_f16_f32 v80, v100, v101
	v_pk_mul_f32 v[100:101], v[48:49], s[100:101] op_sel_hi:[1,0]
	v_exp_f32_e32 v100, v100
	v_exp_f32_e32 v101, v101
	v_cvt_pk_f16_f32 v81, v102, v103
	v_cvt_pk_f16_f32 v83, v112, v113
	global_store_dwordx4 v105, v[80:83], s[14:15] nt
	v_pk_fma_f32 v[74:75], v[74:75], v[162:163], v[160:161]
	v_pk_mul_f32 v[160:161], v[66:67], v[192:193]
	v_pk_add_f32 v[80:81], v[100:101], 1.0 op_sel_hi:[1,0]
	v_rcp_f32_e32 v80, v80
	v_rcp_f32_e32 v81, v81
	v_pk_mul_f32 v[82:83], v[50:51], s[100:101] op_sel_hi:[1,0]
	v_exp_f32_e32 v82, v82
	v_pk_mul_f32 v[48:49], v[48:49], v[80:81]
	v_pk_mul_f32 v[80:81], v[72:73], s[100:101] op_sel_hi:[1,0]
	v_exp_f32_e32 v80, v80
	v_exp_f32_e32 v81, v81
	v_exp_f32_e32 v83, v83
	v_pk_add_f32 v[80:81], v[80:81], 1.0 op_sel_hi:[1,0]
	v_rcp_f32_e32 v80, v80
	v_rcp_f32_e32 v81, v81
	v_pk_add_f32 v[82:83], v[82:83], 1.0 op_sel_hi:[1,0]
	v_rcp_f32_e32 v82, v82
	v_rcp_f32_e32 v83, v83
	v_pk_fma_f32 v[74:75], v[66:67], v[166:167], v[74:75]
	v_pk_mul_f32 v[72:73], v[72:73], v[80:81]
	v_pk_mul_f32 v[80:81], v[74:75], s[100:101] op_sel_hi:[1,0]
	v_exp_f32_e32 v80, v80
	v_exp_f32_e32 v81, v81
	v_pk_mul_f32 v[50:51], v[50:51], v[82:83]
	v_pk_mul_f32 v[82:83], v[30:31], v[20:21]
;     __device__ bool next(int i, Unit& u) const { return S.next(i, u); }
;     __device__ bool next(int i, Unit& u) const { const int L = i * G + c; if (L >= 3 * 44) return false; u.pm = L % 3; u.pn = L / 3; u.g = 0; u.part = 0; u.keep = 0; return true; }
; __device__ __forceinline__ float silu_f(float x) { return x * __builtin_amdgcn_rcpf(1.0f + __expf(-x)); }
;     __device__ __forceinline__ void operator()(Acc& acc, const Unit& u, int wr, int wc, int fr, int fq, LAS unsigned char* lds, int tid) const {
;     ...
;                 for (int e = 0; e < 4; ++e) {
;                     const float prev = dpp_shr1(hl[e], acc[1][bj][3][n][e]);
;                     const float next = dpp_shl1(hr[e], acc[0][bj][0][n][e]);
;                     float left = prev;
; #pragma unroll
;                     for (int j = 0; j < 8; ++j) {
;                         const float cur = acc[j >> 2][bj][j & 3][n][e];
;                         const float nx = (j < 7) ? acc[(j + 1) >> 2][bj][(j + 1) & 3][n][e] : next;
;                         acc[j >> 2][bj][j & 3][n][e] = c0[e] * left + c1[e] * cur + c2[e] * nx;
;                         left = cur;
;                     }
;     ...
;         const unsigned colo = u.pn * 128 + wc * 32 + 8 * fq;
; #pragma unroll
;         for (int ai = 0; ai < 2; ++ai)
; #pragma unroll
;             for (int m = 0; m < 4; ++m) {
;                 f32x4 a[2];
; #pragma unroll
;                 for (int n = 0; n < 2; ++n)
; #pragma unroll
;                     for (int e = 0; e < 4; ++e) a[n][e] = silu_f(acc[ai][0][m][n][e]) * acc[ai][1][m][n][e];
;                 store_h8_nt((h16*)((char*)ACT + (((tok0 + tl0 + 4u * ai + m) * (unsigned)FF + colo) << 1)), a[0], a[1]);
;                 asm volatile("" ::: "memory");
;             }
	v_pk_mul_f32 v[48:49], v[48:49], v[96:97]
	v_pk_fma_f32 v[54:55], v[54:55], v[18:19], v[82:83]
	v_pk_mul_f32 v[50:51], v[50:51], v[98:99]
	v_pk_fma_f32 v[54:55], v[26:27], v[22:23], v[54:55]
	v_cvt_pk_f16_f32 v48, v48, v49
	v_pk_mul_f32 v[54:55], v[72:73], v[54:55]
	v_pk_add_f32 v[72:73], v[80:81], 1.0 op_sel_hi:[1,0]
	v_rcp_f32_e32 v72, v72
	v_rcp_f32_e32 v73, v73
	v_pk_mul_f32 v[80:81], v[28:29], v[12:13]
	v_cvt_pk_f16_f32 v49, v50, v51
	v_pk_fma_f32 v[52:53], v[52:53], v[10:11], v[80:81]
	v_pk_mul_f32 v[72:73], v[74:75], v[72:73]
	v_pk_fma_f32 v[52:53], v[24:25], v[14:15], v[52:53]
	v_cvt_pk_f16_f32 v50, v54, v55
	v_pk_mul_f32 v[52:53], v[72:73], v[52:53]
	v_add_u32_e32 v72, 0x8400, v104
	v_cvt_pk_f16_f32 v51, v52, v53
	v_pk_mul_f32 v[52:53], v[44:45], s[100:101] op_sel_hi:[1,0]
	v_exp_f32_e32 v52, v52
	v_exp_f32_e32 v53, v53
	global_store_dwordx4 v72, v[48:51], s[14:15] nt
	v_pk_fma_f32 v[70:71], v[70:71], v[162:163], v[160:161]
	v_pk_mul_f32 v[160:161], v[62:63], v[192:193]
	v_pk_add_f32 v[48:49], v[52:53], 1.0 op_sel_hi:[1,0]
	v_pk_mul_f32 v[50:51], v[46:47], s[100:101] op_sel_hi:[1,0]
	v_rcp_f32_e32 v48, v48
	v_exp_f32_e32 v50, v50
	v_exp_f32_e32 v51, v51
	v_rcp_f32_e32 v49, v49
	v_pk_fma_f32 v[70:71], v[62:63], v[166:167], v[70:71]
	v_pk_add_f32 v[50:51], v[50:51], 1.0 op_sel_hi:[1,0]
	v_pk_mul_f32 v[44:45], v[44:45], v[48:49]
	v_pk_mul_f32 v[48:49], v[68:69], s[100:101] op_sel_hi:[1,0]
	v_rcp_f32_e32 v50, v50
	v_rcp_f32_e32 v51, v51
	v_exp_f32_e32 v48, v48
	v_exp_f32_e32 v49, v49
	v_pk_mul_f32 v[44:45], v[44:45], v[92:93]
	v_pk_mul_f32 v[46:47], v[46:47], v[50:51]
	v_pk_add_f32 v[48:49], v[48:49], 1.0 op_sel_hi:[1,0]
	v_pk_mul_f32 v[50:51], v[26:27], v[20:21]
	v_rcp_f32_e32 v48, v48
	v_rcp_f32_e32 v49, v49
	v_pk_fma_f32 v[30:31], v[30:31], v[18:19], v[50:51]
	v_pk_mul_f32 v[50:51], v[70:71], s[100:101] op_sel_hi:[1,0]
	v_exp_f32_e32 v50, v50
	v_exp_f32_e32 v51, v51
	v_pk_fma_f32 v[30:31], v[16:17], v[22:23], v[30:31]
	v_pk_mul_f32 v[48:49], v[68:69], v[48:49]
	v_pk_mul_f32 v[46:47], v[46:47], v[94:95]
	v_pk_mul_f32 v[30:31], v[48:49], v[30:31]
	v_pk_add_f32 v[48:49], v[50:51], 1.0 op_sel_hi:[1,0]
	v_rcp_f32_e32 v48, v48
	v_rcp_f32_e32 v49, v49
	v_pk_mul_f32 v[50:51], v[24:25], v[12:13]
	v_cvt_pk_f16_f32 v30, v30, v31
	v_pk_fma_f32 v[28:29], v[28:29], v[10:11], v[50:51]
	v_pk_mul_f32 v[48:49], v[70:71], v[48:49]
	v_pk_fma_f32 v[28:29], v[8:9], v[14:15], v[28:29]
	v_add_u32_e32 v50, 0xb000, v104
	v_pk_mul_f32 v[48:49], v[48:49], v[28:29]
	v_cvt_pk_f16_f32 v28, v44, v45
	v_pk_mul_f32 v[44:45], v[40:41], s[100:101] op_sel_hi:[1,0]
	v_exp_f32_e32 v44, v44
	v_exp_f32_e32 v45, v45
	v_cvt_pk_f16_f32 v29, v46, v47
	v_cvt_pk_f16_f32 v31, v48, v49
	global_store_dwordx4 v50, v[28:31], s[14:15] nt
	v_pk_fma_f32 v[66:67], v[66:67], v[162:163], v[160:161]
	v_pk_fma_f32 v[90:91], v[78:79], v[194:195], v[90:91]
	v_pk_add_f32 v[28:29], v[44:45], 1.0 op_sel_hi:[1,0]
	v_pk_mul_f32 v[30:31], v[42:43], s[100:101] op_sel_hi:[1,0]
	v_rcp_f32_e32 v28, v28
	v_exp_f32_e32 v30, v30
	v_exp_f32_e32 v31, v31
	v_rcp_f32_e32 v29, v29
	v_pk_fma_f32 v[66:67], v[58:59], v[166:167], v[66:67]
	v_pk_add_f32 v[30:31], v[30:31], 1.0 op_sel_hi:[1,0]
	v_pk_mul_f32 v[28:29], v[40:41], v[28:29]
	v_pk_mul_f32 v[40:41], v[64:65], s[100:101] op_sel_hi:[1,0]
	v_rcp_f32_e32 v30, v30
	v_rcp_f32_e32 v31, v31
	v_exp_f32_e32 v40, v40
	v_exp_f32_e32 v41, v41
	v_pk_mul_f32 v[28:29], v[28:29], v[88:89]
	v_pk_mul_f32 v[30:31], v[42:43], v[30:31]
	v_pk_add_f32 v[40:41], v[40:41], 1.0 op_sel_hi:[1,0]
	v_pk_mul_f32 v[42:43], v[16:17], v[20:21]
	v_rcp_f32_e32 v40, v40
	v_rcp_f32_e32 v41, v41
	v_pk_fma_f32 v[26:27], v[26:27], v[18:19], v[42:43]
	v_pk_mul_f32 v[42:43], v[66:67], s[100:101] op_sel_hi:[1,0]
	v_exp_f32_e32 v42, v42
	v_exp_f32_e32 v43, v43
	v_pk_fma_f32 v[26:27], v[2:3], v[22:23], v[26:27]
	v_pk_mul_f32 v[40:41], v[64:65], v[40:41]
	v_pk_mul_f32 v[30:31], v[30:31], v[90:91]
	v_pk_mul_f32 v[26:27], v[40:41], v[26:27]
	v_pk_add_f32 v[40:41], v[42:43], 1.0 op_sel_hi:[1,0]
	v_rcp_f32_e32 v40, v40
	v_rcp_f32_e32 v41, v41
	v_pk_mul_f32 v[42:43], v[8:9], v[12:13]
	v_pk_fma_f32 v[60:61], v[234:235], v[164:165], v[60:61]
	v_pk_fma_f32 v[24:25], v[24:25], v[10:11], v[42:43]
	v_pk_mul_f32 v[40:41], v[66:67], v[40:41]
	v_pk_fma_f32 v[24:25], v[4:5], v[14:15], v[24:25]
	v_add_u32_e32 v42, 0xdc00, v104
	v_pk_mul_f32 v[40:41], v[40:41], v[24:25]
; #define PG8_BAR __builtin_amdgcn_s_barrier()
; __device__ __forceinline__ float silu_f(float x) { return x * __builtin_amdgcn_rcpf(1.0f + __expf(-x)); }
; template <class Prob, class Epi, bool I8 = false, bool ALIGN_EPI = true, bool SP2 = true>
; __device__ __forceinline__ void gemm_phase(LAS unsigned char* lds, int wave, const Prob& P, const Epi& E) {
;     ...
;         if (!has_next) break;
;         if (!cur.keep) {
; #pragma unroll
;         for (int a = 0; a < 2; ++a)
; #pragma unroll
;             for (int b = 0; b < 2; ++b)
; #pragma unroll
;                 for (int m = 0; m < 4; ++m)
; #pragma unroll
;                     for (int n = 0; n < 2; ++n) acc[a][b][m][n] = (f32x4){0.f, 0.f, 0.f, 0.f};
;         }
;         cur = nxt; cA = nA; cB = nB; ++ui;
;         if constexpr (ALIGN_EPI) { if (wr == 1) PG8_BAR; }
;     __device__ __forceinline__ void operator()(Acc& acc, const Unit& u, int wr, int wc, int fr, int fq, LAS unsigned char* lds, int tid) const {
;     ...
;         const unsigned colo = u.pn * 128 + wc * 32 + 8 * fq;
; #pragma unroll
;         for (int ai = 0; ai < 2; ++ai)
; #pragma unroll
;             for (int m = 0; m < 4; ++m) {
;                 f32x4 a[2];
; #pragma unroll
;                 for (int n = 0; n < 2; ++n)
; #pragma unroll
;                     for (int e = 0; e < 4; ++e) a[n][e] = silu_f(acc[ai][0][m][n][e]) * acc[ai][1][m][n][e];
;                 store_h8_nt((h16*)((char*)ACT + (((tok0 + tl0 + 4u * ai + m) * (unsigned)FF + colo) << 1)), a[0], a[1]);
;                 asm volatile("" ::: "memory");
;             }
	v_cvt_pk_f16_f32 v24, v28, v29
	v_pk_mul_f32 v[28:29], v[36:37], s[100:101] op_sel_hi:[1,0]
	v_exp_f32_e32 v28, v28
	v_exp_f32_e32 v29, v29
	v_cvt_pk_f16_f32 v25, v30, v31
	v_cvt_pk_f16_f32 v26, v26, v27
	v_cvt_pk_f16_f32 v27, v40, v41
	global_store_dwordx4 v42, v[24:27], s[14:15] nt
	v_pk_mul_f32 v[160:161], v[58:59], v[192:193]
	v_pk_mul_f32 v[30:31], v[2:3], v[20:21]
	v_pk_add_f32 v[24:25], v[28:29], 1.0 op_sel_hi:[1,0]
	v_pk_mul_f32 v[28:29], v[60:61], s[100:101] op_sel_hi:[1,0]
	v_exp_f32_e32 v28, v28
	v_exp_f32_e32 v29, v29
	v_pk_fma_f32 v[62:63], v[62:63], v[162:163], v[160:161]
	v_pk_fma_f32 v[62:63], v[230:231], v[166:167], v[62:63]
	v_pk_add_f32 v[28:29], v[28:29], 1.0 op_sel_hi:[1,0]
	v_pk_mul_f32 v[26:27], v[38:39], s[100:101] op_sel_hi:[1,0]
	v_rcp_f32_e32 v28, v28
	v_rcp_f32_e32 v29, v29
	v_pk_fma_f32 v[16:17], v[16:17], v[18:19], v[30:31]
	v_pk_mul_f32 v[30:31], v[62:63], s[100:101] op_sel_hi:[1,0]
	v_exp_f32_e32 v26, v26
	v_exp_f32_e32 v27, v27
	v_exp_f32_e32 v30, v30
	v_exp_f32_e32 v31, v31
	v_pk_fma_f32 v[16:17], v[6:7], v[22:23], v[16:17]
	v_pk_mul_f32 v[28:29], v[60:61], v[28:29]
	v_pk_add_f32 v[26:27], v[26:27], 1.0 op_sel_hi:[1,0]
	v_pk_mul_f32 v[16:17], v[28:29], v[16:17]
	v_pk_add_f32 v[28:29], v[30:31], 1.0 op_sel_hi:[1,0]
	v_rcp_f32_e32 v24, v24
	v_rcp_f32_e32 v25, v25
	v_rcp_f32_e32 v26, v26
	v_rcp_f32_e32 v27, v27
	v_rcp_f32_e32 v28, v28
	v_rcp_f32_e32 v29, v29
	v_pk_mul_f32 v[30:31], v[4:5], v[12:13]
	v_pk_fma_f32 v[86:87], v[238:239], v[194:195], v[86:87]
	v_pk_fma_f32 v[8:9], v[8:9], v[10:11], v[30:31]
	v_pk_mul_f32 v[24:25], v[36:37], v[24:25]
	v_pk_mul_f32 v[26:27], v[38:39], v[26:27]
	v_pk_fma_f32 v[8:9], v[0:1], v[14:15], v[8:9]
	v_pk_mul_f32 v[28:29], v[62:63], v[28:29]
	v_pk_mul_f32 v[24:25], v[24:25], v[84:85]
	v_pk_mul_f32 v[26:27], v[26:27], v[86:87]
	v_pk_mul_f32 v[8:9], v[28:29], v[8:9]
	v_pk_fma_f32 v[56:57], v[164:165], v[172:173], v[56:57]
	v_add_u32_e32 v28, 0x10800, v104
	v_cvt_pk_f16_f32 v24, v24, v25
	v_cvt_pk_f16_f32 v25, v26, v27
	v_cvt_pk_f16_f32 v26, v16, v17
	v_cvt_pk_f16_f32 v27, v8, v9
	global_store_dwordx4 v28, v[24:27], s[14:15] nt
	v_pk_mul_f32 v[58:59], v[58:59], v[162:163]
	s_nop 0
	v_pk_mul_f32 v[24:25], v[56:57], s[100:101] op_sel_hi:[1,0]
	v_exp_f32_e32 v24, v24
	v_exp_f32_e32 v25, v25
	v_pk_fma_f32 v[58:59], v[230:231], v[192:193], v[58:59]
	v_pk_mul_f32 v[8:9], v[32:33], s[100:101] op_sel_hi:[1,0]
	v_pk_fma_f32 v[58:59], v[166:167], v[174:175], v[58:59]
	v_pk_add_f32 v[24:25], v[24:25], 1.0 op_sel_hi:[1,0]
	v_pk_mul_f32 v[16:17], v[34:35], s[100:101] op_sel_hi:[1,0]
	v_rcp_f32_e32 v24, v24
	v_rcp_f32_e32 v25, v25
	v_pk_mul_f32 v[2:3], v[2:3], v[18:19]
	v_pk_mul_f32 v[18:19], v[58:59], s[100:101] op_sel_hi:[1,0]
	v_exp_f32_e32 v8, v8
	v_exp_f32_e32 v9, v9
	v_exp_f32_e32 v16, v16
	v_exp_f32_e32 v17, v17
	v_exp_f32_e32 v18, v18
	v_exp_f32_e32 v19, v19
	v_mov_b32_dpp v108, v134 row_shl:1 row_mask:0xf bank_mask:0xf
	v_mov_b32_dpp v109, v135 row_shl:1 row_mask:0xf bank_mask:0xf
	v_pk_fma_f32 v[2:3], v[6:7], v[20:21], v[2:3]
	v_pk_mul_f32 v[6:7], v[56:57], v[24:25]
	v_pk_fma_f32 v[2:3], v[22:23], v[108:109], v[2:3]
	v_pk_add_f32 v[8:9], v[8:9], 1.0 op_sel_hi:[1,0]
	v_pk_add_f32 v[16:17], v[16:17], 1.0 op_sel_hi:[1,0]
	v_pk_mul_f32 v[2:3], v[6:7], v[2:3]
	v_pk_add_f32 v[6:7], v[18:19], 1.0 op_sel_hi:[1,0]
	v_rcp_f32_e32 v8, v8
	v_rcp_f32_e32 v9, v9
	v_rcp_f32_e32 v16, v16
	v_rcp_f32_e32 v17, v17
	v_rcp_f32_e32 v6, v6
	v_rcp_f32_e32 v7, v7
	v_pk_mul_f32 v[78:79], v[78:79], v[214:215]
	v_pk_mul_f32 v[4:5], v[4:5], v[10:11]
	v_pk_fma_f32 v[78:79], v[238:239], v[198:199], v[78:79]
	v_pk_fma_f32 v[0:1], v[0:1], v[12:13], v[4:5]
	v_pk_fma_f32 v[78:79], v[194:195], v[206:207], v[78:79]
	v_pk_mul_f32 v[8:9], v[32:33], v[8:9]
	v_pk_mul_f32 v[16:17], v[34:35], v[16:17]
	v_pk_fma_f32 v[0:1], v[14:15], v[110:111], v[0:1]
	v_pk_mul_f32 v[4:5], v[58:59], v[6:7]
	v_pk_mul_f32 v[8:9], v[8:9], v[76:77]
	v_pk_mul_f32 v[16:17], v[16:17], v[78:79]
	v_pk_mul_f32 v[4:5], v[4:5], v[0:1]
	v_add_u32_e32 v6, 0x13400, v104
	v_cvt_pk_f16_f32 v0, v8, v9
	v_cvt_pk_f16_f32 v1, v16, v17
	v_cvt_pk_f16_f32 v2, v2, v3
	v_cvt_pk_f16_f32 v3, v4, v5
	global_store_dwordx4 v6, v[0:3], s[14:15] nt
	s_cmp_eq_u32 s101, 0
	s_cbranch_scc1 .Lh1065_exit
	s_cmp_eq_u64 s[16:17], 0
	s_cbranch_scc1 .Lpeel_1065
	s_barrier
	s_branch .Lpeel_1065
